# P0: conversion tiles beyond the first 5*256 go only to blocks without a modulation GEMV task (stride 112)
# speedup vs baseline: 1.0137x; 1.0083x over previous
.LBB0_17:
	s_not_b32 s4, s2
	s_add_i32 s68, s42, s4
	s_mov_b32 s90, s42
	s_cmpk_gt_i32 s68, 0xa1f
	s_cbranch_scc1 .LBB0_52
	s_add_u32 s14, s38, 0x4900000
	s_addc_u32 s15, s39, 0
	s_add_u32 s16, s38, 0x4700000
	s_addc_u32 s17, s39, 0
	s_load_dwordx2 s[10:11], s[0:1], 0xa0
	s_load_dwordx2 s[12:13], s[0:1], 0x90
	s_load_dwordx4 s[4:7], s[0:1], 0x58
	s_add_u32 s18, s38, 0x4200000
	s_addc_u32 s19, s39, 0
	s_add_u32 s20, s38, 0x4f00000
	s_addc_u32 s21, s39, 0
	s_add_u32 s69, s38, 0x2c00000
	s_addc_u32 s70, s39, 0
	s_movk_i32 s71, 0x800
	v_mov_b32_e32 v3, 0
	s_movk_i32 s72, 0x204
	s_movk_i32 s73, 0x3ff
	s_movk_i32 s74, 0x200
	s_movk_i32 s75, 0xb00
	v_mov_b32_e32 v4, 0x80
	s_branch .LBB0_21

.LBB0_20:
	v_lshlrev_b32_e32 v2, 5, v5
	v_and_b32_e32 v5, 0x60, v2
	v_ashrrev_i32_e32 v2, 31, v7
	v_mul_lo_u32 v10, s25, v7
	v_mul_lo_u32 v2, s24, v2
	v_mad_u64_u32 v[8:9], s[24:25], s24, v7, 0
	v_add3_u32 v9, v9, v2, v10
	v_lshlrev_b32_e32 v2, 1, v5
	v_lshlrev_b32_e32 v6, 2, v6
	v_mul_u32_u24_e32 v5, 0x204, v5
	v_lshl_add_u64 v[8:9], v[8:9], 1, s[22:23]
	s_ashr_i32 s29, s28, 31
	v_add3_u32 v5, 0, v6, v5
	v_lshl_add_u64 v[8:9], s[28:29], 1, v[8:9]
	v_add_u32_e32 v10, 0x400, v5
	ds_read2_b32 v[6:7], v5 offset1:129
	ds_read2_b32 v[10:11], v10 offset0:2 offset1:131
	v_add_u32_e32 v12, 0x800, v5
	v_add_u32_e32 v14, 0xc00, v5
	v_lshl_add_u64 v[16:17], v[8:9], 0, v[2:3]
	v_add_u32_e32 v2, 0x1000, v5
	ds_read2_b32 v[12:13], v12 offset0:4 offset1:133
	ds_read2_b32 v[14:15], v14 offset0:6 offset1:135
	s_waitcnt lgkmcnt(3)
	v_cvt_pk_bf16_f32 v6, v6, v7
	s_waitcnt lgkmcnt(2)
	v_cvt_pk_bf16_f32 v7, v10, v11
	s_waitcnt lgkmcnt(1)
	v_cvt_pk_bf16_f32 v8, v12, v13
	s_waitcnt lgkmcnt(0)
	v_cvt_pk_bf16_f32 v9, v14, v15
	ds_read2_b32 v[10:11], v2 offset0:8 offset1:137
	v_add_u32_e32 v2, 0x1400, v5
	ds_read2_b32 v[12:13], v2 offset0:10 offset1:139
	v_add_u32_e32 v2, 0x1800, v5
	ds_read2_b32 v[14:15], v2 offset0:12 offset1:141
	v_add_u32_e32 v2, 0x1c00, v5
	ds_read2_b32 v[18:19], v2 offset0:14 offset1:143
	v_add_u32_e32 v2, 0x2000, v5
	global_store_dwordx4 v[16:17], v[6:9], off
	s_add_i32 s68, s68, s90
	s_cmp_lg_u32 s90, s42
	s_cbranch_scc1 .Lmy_p0_nomap
	s_cmpk_lt_i32 s68, 1280
	s_cbranch_scc1 .Lmy_p0_nomap
	s_sub_i32 s91, s68, 1280
	s_cmpk_gt_i32 s91, 111
	s_cselect_b32 s68, 0x7fff, s68
	s_movk_i32 s90, 112
.Lmy_p0_nomap:
	s_cmpk_lt_i32 s68, 0xa20
	s_waitcnt lgkmcnt(3)
	v_cvt_pk_bf16_f32 v6, v10, v11
	s_waitcnt lgkmcnt(2)
	v_cvt_pk_bf16_f32 v7, v12, v13
	s_waitcnt lgkmcnt(1)
	v_cvt_pk_bf16_f32 v8, v14, v15
	s_waitcnt lgkmcnt(0)
	v_cvt_pk_bf16_f32 v9, v18, v19
	ds_read2_b32 v[10:11], v2 offset0:16 offset1:145
	v_add_u32_e32 v2, 0x2400, v5
	ds_read2_b32 v[12:13], v2 offset0:18 offset1:147
	v_add_u32_e32 v2, 0x2800, v5
	ds_read2_b32 v[14:15], v2 offset0:20 offset1:149
	v_add_u32_e32 v2, 0x2c00, v5
	ds_read2_b32 v[18:19], v2 offset0:22 offset1:151
	v_add_u32_e32 v2, 0x3000, v5
	global_store_dwordx4 v[16:17], v[6:9], off offset:16
	s_waitcnt lgkmcnt(3)
	s_nop 0
	v_cvt_pk_bf16_f32 v6, v10, v11
	s_waitcnt lgkmcnt(2)
	v_cvt_pk_bf16_f32 v7, v12, v13
	s_waitcnt lgkmcnt(1)
	v_cvt_pk_bf16_f32 v8, v14, v15
	s_waitcnt lgkmcnt(0)
	v_cvt_pk_bf16_f32 v9, v18, v19
	ds_read2_b32 v[10:11], v2 offset0:24 offset1:153
	v_add_u32_e32 v2, 0x3400, v5
	ds_read2_b32 v[12:13], v2 offset0:26 offset1:155
	v_add_u32_e32 v2, 0x3800, v5
	ds_read2_b32 v[14:15], v2 offset0:28 offset1:157
	v_add_u32_e32 v2, 0x3c00, v5
	ds_read2_b32 v[18:19], v2 offset0:30 offset1:159
	global_store_dwordx4 v[16:17], v[6:9], off offset:32
	s_waitcnt lgkmcnt(3)
	s_nop 0
	v_cvt_pk_bf16_f32 v6, v10, v11
	s_waitcnt lgkmcnt(2)
	v_cvt_pk_bf16_f32 v7, v12, v13
	s_waitcnt lgkmcnt(1)
	v_cvt_pk_bf16_f32 v8, v14, v15
	s_waitcnt lgkmcnt(0)
	v_cvt_pk_bf16_f32 v9, v18, v19
	global_store_dwordx4 v[16:17], v[6:9], off offset:48
	s_barrier
	s_cbranch_scc0 .LBB0_52

	.amdhsa_kernel _Z10fwd_kernel4Args
		.amdhsa_group_segment_fixed_size 0
		.amdhsa_private_segment_fixed_size 0
		.amdhsa_kernarg_size 448
		.amdhsa_user_sgpr_count 2
		.amdhsa_user_sgpr_dispatch_ptr 0
		.amdhsa_user_sgpr_queue_ptr 0
		.amdhsa_user_sgpr_kernarg_segment_ptr 1
		.amdhsa_user_sgpr_dispatch_id 0
		.amdhsa_user_sgpr_kernarg_preload_length 0
		.amdhsa_user_sgpr_kernarg_preload_offset 0
		.amdhsa_user_sgpr_private_segment_size 0
		.amdhsa_uses_dynamic_stack 0
		.amdhsa_enable_private_segment 0
		.amdhsa_system_sgpr_workgroup_id_x 1
		.amdhsa_system_sgpr_workgroup_id_y 0
		.amdhsa_system_sgpr_workgroup_id_z 0
		.amdhsa_system_sgpr_workgroup_info 0
		.amdhsa_system_vgpr_workitem_id 2
		.amdhsa_next_free_vgpr 240
		.amdhsa_next_free_sgpr 96
		.amdhsa_accum_offset 240
		.amdhsa_reserve_vcc 1
		.amdhsa_float_round_mode_32 0
		.amdhsa_float_round_mode_16_64 0
		.amdhsa_float_denorm_mode_32 3
		.amdhsa_float_denorm_mode_16_64 3
		.amdhsa_dx10_clamp 1
		.amdhsa_ieee_mode 1
		.amdhsa_fp16_overflow 0
		.amdhsa_tg_split 0
		.amdhsa_exception_fp_ieee_invalid_op 0
		.amdhsa_exception_fp_denorm_src 0
		.amdhsa_exception_fp_ieee_div_zero 0
		.amdhsa_exception_fp_ieee_overflow 0
		.amdhsa_exception_fp_ieee_underflow 0
		.amdhsa_exception_fp_ieee_inexact 0
		.amdhsa_exception_int_div_zero 0
	.end_amdhsa_kernel

amdhsa.kernels:
  - .agpr_count:     0
    .args:
      - .offset:         0
        .size:           192
        .value_kind:     by_value
      - .offset:         192
        .size:           4
        .value_kind:     hidden_block_count_x
      - .offset:         196
        .size:           4
        .value_kind:     hidden_block_count_y
      - .offset:         200
        .size:           4
        .value_kind:     hidden_block_count_z
      - .offset:         204
        .size:           2
        .value_kind:     hidden_group_size_x
      - .offset:         206
        .size:           2
        .value_kind:     hidden_group_size_y
      - .offset:         208
        .size:           2
        .value_kind:     hidden_group_size_z
      - .offset:         210
        .size:           2
        .value_kind:     hidden_remainder_x
      - .offset:         212
        .size:           2
        .value_kind:     hidden_remainder_y
      - .offset:         214
        .size:           2
        .value_kind:     hidden_remainder_z
      - .offset:         232
        .size:           8
        .value_kind:     hidden_global_offset_x
      - .offset:         240
        .size:           8
        .value_kind:     hidden_global_offset_y
      - .offset:         248
        .size:           8
        .value_kind:     hidden_global_offset_z
      - .offset:         256
        .size:           2
        .value_kind:     hidden_grid_dims
      - .offset:         280
        .size:           8
        .value_kind:     hidden_multigrid_sync_arg
      - .offset:         312
        .size:           4
        .value_kind:     hidden_dynamic_lds_size
    .group_segment_fixed_size: 0
    .kernarg_segment_align: 8
    .kernarg_segment_size: 448
    .language:       OpenCL C
    .language_version:
      - 2
      - 0
    .max_flat_workgroup_size: 512
    .name:           _Z10fwd_kernel4Args
    .private_segment_fixed_size: 0
    .sgpr_count:     102
    .sgpr_spill_count: 0
    .symbol:         _Z10fwd_kernel4Args.kd
    .uniform_work_group_size: 1
    .uses_dynamic_stack: false
    .vgpr_count:     240
    .vgpr_spill_count: 0
    .wavefront_size: 64
